# GEMM K-loop heads placed at 44 mod 64 bytes
# baseline (speedup 1.0000x reference)
;   __device__ __forceinline__ const char* aptr(const Unit& u) const { return s.aptr(u); }
;   __device__ __forceinline__ const char* bptr(const Unit& u) const { return s.bptr(u); }
;   __device__ __forceinline__ bool next(int i, Unit& u) const { if (i) return false; u = u0; return true; }
; template <class Epi, class Sched>
; __device__ __forceinline__ void gemm_phase(PG8_LAS unsigned char* lds, const int lda, const int ldb, const Sched& S, const Epi& E) {
;     ...
;     const bool has_next = S.next(ui + 1, nxt);
;     const char* nA = has_next ? S.aptr(nxt) : cA; const char* nB = has_next ? S.bptr(nxt) : cB;
; #pragma unroll 1
;     for (int t = 0; t < nt; t += 2) {
;       const bool last = (t == nt - 2);
;       const char* a1 = cA + (size_t)(t + 1) * kstep;
;       const char* a2 = last ? nA : cA + (size_t)(t + 2) * kstep; const char* b2 = last ? nB : cB + (size_t)(t + 2) * kstep;
;     ...
;     for (int a = 0; a < 2; ++a)
; #pragma unroll
;       for (int b = 0; b < 2; ++b)
; #pragma unroll
;         for (int m = 0; m < 4; ++m)
; #pragma unroll
;           for (int n = 0; n < 2; ++n) acc[a][b][m][n] = (f32x4){0.f, 0.f, 0.f, 0.f};
.LBB0_334:
	s_ashr_i32 s17, s16, 31
	s_xor_b64 s[20:21], s[24:25], -1
	s_lshl_b64 s[18:19], s[16:17], 19
	s_add_u32 s18, s58, s18
	s_addc_u32 s19, s59, s19
	s_and_b64 s[22:23], s[24:25], exec
	s_cselect_b32 s17, s19, s9
	s_cselect_b32 s26, s18, s8
	s_ashr_i32 s15, s14, 31
	s_lshl_b64 s[22:23], s[14:15], 19
	v_readlane_b32 s15, v255, 29
	s_add_u32 s22, s15, s22
	v_readlane_b32 s15, v255, 30
	s_addc_u32 s23, s15, s23
	s_and_b64 s[24:25], s[24:25], exec
	s_cselect_b32 s15, s23, s11
	s_cselect_b32 s27, s22, s10
	s_add_u32 s8, s8, 0x40080
	s_addc_u32 s9, s9, 0
	s_add_u32 s28, s10, 0x100
	v_mov_b32_e32 v2, 0
	s_addc_u32 s29, s11, 0
	s_mov_b32 s30, -2
	v_mov_b32_e32 v3, v2
	v_mov_b64_e32 v[4:5], 0
	v_mov_b64_e32 v[6:7], 0
	v_mov_b64_e32 v[8:9], 0
	v_mov_b64_e32 v[10:11], 0
	v_mov_b64_e32 v[12:13], 0
	v_mov_b64_e32 v[14:15], 0
	v_mov_b64_e32 v[16:17], 0
	v_mov_b64_e32 v[18:19], 0
	v_mov_b64_e32 v[20:21], 0
	v_mov_b64_e32 v[22:23], 0
	v_mov_b64_e32 v[24:25], 0
	v_mov_b64_e32 v[26:27], 0
	v_mov_b64_e32 v[28:29], 0
	v_mov_b64_e32 v[30:31], 0
	v_mov_b64_e32 v[32:33], 0
	v_mov_b64_e32 v[34:35], 0
	v_mov_b64_e32 v[36:37], 0
	v_mov_b64_e32 v[38:39], 0
	v_mov_b64_e32 v[40:41], 0
	v_mov_b64_e32 v[42:43], 0
	v_mov_b64_e32 v[44:45], 0
	v_mov_b64_e32 v[46:47], 0
	v_mov_b64_e32 v[48:49], 0
	v_mov_b64_e32 v[50:51], 0
	v_mov_b64_e32 v[52:53], 0
	v_mov_b64_e32 v[54:55], 0
	v_mov_b64_e32 v[56:57], 0
	v_mov_b64_e32 v[58:59], 0
	v_mov_b64_e32 v[60:61], 0
	v_mov_b64_e32 v[62:63], 0
	v_mov_b64_e32 v[64:65], 0
	v_mov_b64_e32 v[66:67], 0
	v_mov_b64_e32 v[68:69], 0
	v_mov_b64_e32 v[70:71], 0
	v_mov_b64_e32 v[72:73], 0
	v_mov_b64_e32 v[74:75], 0
	v_mov_b64_e32 v[76:77], 0
	v_mov_b64_e32 v[78:79], 0
	v_mov_b64_e32 v[80:81], 0
	v_mov_b64_e32 v[82:83], 0
	v_mov_b64_e32 v[84:85], 0
	v_mov_b64_e32 v[86:87], 0
	v_mov_b64_e32 v[88:89], 0
	v_mov_b64_e32 v[90:91], 0
	v_mov_b64_e32 v[92:93], 0
	v_mov_b64_e32 v[94:95], 0
	v_mov_b64_e32 v[96:97], 0
	v_mov_b64_e32 v[98:99], 0
	v_mov_b64_e32 v[100:101], 0
	v_mov_b64_e32 v[102:103], 0
	v_mov_b64_e32 v[104:105], 0
	v_mov_b64_e32 v[106:107], 0
	v_mov_b64_e32 v[108:109], 0
	v_mov_b64_e32 v[110:111], 0
	v_mov_b64_e32 v[112:113], 0
	v_mov_b64_e32 v[114:115], 0
	v_mov_b64_e32 v[116:117], 0
	v_mov_b64_e32 v[118:119], 0
	v_mov_b64_e32 v[120:121], 0
	v_mov_b64_e32 v[122:123], 0
	v_mov_b64_e32 v[124:125], 0
	v_mov_b64_e32 v[126:127], 0
	v_mov_b64_e32 v[128:129], 0
	.p2align	6
	s_nop 0
	s_nop 0
	s_nop 0
	s_nop 0
	s_nop 0
	s_nop 0
	s_nop 0
	s_nop 0
	s_nop 0
	s_nop 0
	s_nop 0

;   __device__ __forceinline__ const char* aptr(const Unit& u) const { return s.aptr(u); }
;   __device__ __forceinline__ const char* bptr(const Unit& u) const { return s.bptr(u); }
;   __device__ __forceinline__ bool next(int i, Unit& u) const { if (i) return false; u = u0; return true; }
; template <class Epi, class Sched>
; __device__ __forceinline__ void gemm_phase(PG8_LAS unsigned char* lds, const int lda, const int ldb, const Sched& S, const Epi& E) {
;     ...
;     const bool has_next = S.next(ui + 1, nxt);
;     const char* nA = has_next ? S.aptr(nxt) : cA; const char* nB = has_next ? S.bptr(nxt) : cB;
; #pragma unroll 1
;     for (int t = 0; t < nt; t += 2) {
;       const bool last = (t == nt - 2);
;       const char* a1 = cA + (size_t)(t + 1) * kstep;
;       const char* a2 = last ? nA : cA + (size_t)(t + 2) * kstep; const char* b2 = last ? nB : cB + (size_t)(t + 2) * kstep;
;     ...
;     for (int a = 0; a < 2; ++a)
; #pragma unroll
;       for (int b = 0; b < 2; ++b)
; #pragma unroll
;         for (int m = 0; m < 4; ++m)
; #pragma unroll
;           for (int n = 0; n < 2; ++n) acc[a][b][m][n] = (f32x4){0.f, 0.f, 0.f, 0.f};
.LBB0_684:
	v_mov_b64_e32 v[2:3], 0xa20
	s_ashr_i32 s19, s18, 31
	v_cmp_lt_i64_e32 vcc, s[20:21], v[2:3]
	s_lshl_b64 s[20:21], s[18:19], 19
	s_add_u32 s20, s58, s20
	s_addc_u32 s21, s59, s21
	s_and_b64 s[22:23], vcc, exec
	s_cselect_b32 s19, s21, s11
	s_cselect_b32 s26, s20, s10
	s_ashr_i32 s17, s16, 31
	s_lshl_b64 s[22:23], s[16:17], 19
	v_readlane_b32 s17, v255, 29
	s_add_u32 s22, s17, s22
	v_readlane_b32 s17, v255, 30
	s_addc_u32 s23, s17, s23
	s_and_b64 s[24:25], vcc, exec
	s_cselect_b32 s17, s23, s13
	s_cselect_b32 s27, s22, s12
	s_add_u32 s10, s10, 0x40080
	s_addc_u32 s11, s11, 0
	s_add_u32 s28, s12, 0x100
	v_mov_b32_e32 v2, 0
	s_addc_u32 s29, s13, 0
	s_mov_b32 s30, -2
	v_mov_b32_e32 v3, v2
	v_mov_b64_e32 v[4:5], 0
	v_mov_b64_e32 v[6:7], 0
	v_mov_b64_e32 v[8:9], 0
	v_mov_b64_e32 v[10:11], 0
	v_mov_b64_e32 v[12:13], 0
	v_mov_b64_e32 v[14:15], 0
	v_mov_b64_e32 v[16:17], 0
	v_mov_b64_e32 v[18:19], 0
	v_mov_b64_e32 v[20:21], 0
	v_mov_b64_e32 v[22:23], 0
	v_mov_b64_e32 v[24:25], 0
	v_mov_b64_e32 v[26:27], 0
	v_mov_b64_e32 v[28:29], 0
	v_mov_b64_e32 v[30:31], 0
	v_mov_b64_e32 v[32:33], 0
	v_mov_b64_e32 v[34:35], 0
	v_mov_b64_e32 v[36:37], 0
	v_mov_b64_e32 v[38:39], 0
	v_mov_b64_e32 v[40:41], 0
	v_mov_b64_e32 v[42:43], 0
	v_mov_b64_e32 v[44:45], 0
	v_mov_b64_e32 v[46:47], 0
	v_mov_b64_e32 v[48:49], 0
	v_mov_b64_e32 v[50:51], 0
	v_mov_b64_e32 v[52:53], 0
	v_mov_b64_e32 v[54:55], 0
	v_mov_b64_e32 v[56:57], 0
	v_mov_b64_e32 v[58:59], 0
	v_mov_b64_e32 v[60:61], 0
	v_mov_b64_e32 v[62:63], 0
	v_mov_b64_e32 v[64:65], 0
	v_mov_b64_e32 v[66:67], 0
	v_mov_b64_e32 v[68:69], 0
	v_mov_b64_e32 v[70:71], 0
	v_mov_b64_e32 v[72:73], 0
	v_mov_b64_e32 v[74:75], 0
	v_mov_b64_e32 v[76:77], 0
	v_mov_b64_e32 v[78:79], 0
	v_mov_b64_e32 v[80:81], 0
	v_mov_b64_e32 v[82:83], 0
	v_mov_b64_e32 v[84:85], 0
	v_mov_b64_e32 v[86:87], 0
	v_mov_b64_e32 v[88:89], 0
	v_mov_b64_e32 v[90:91], 0
	v_mov_b64_e32 v[92:93], 0
	v_mov_b64_e32 v[94:95], 0
	v_mov_b64_e32 v[96:97], 0
	v_mov_b64_e32 v[98:99], 0
	v_mov_b64_e32 v[100:101], 0
	v_mov_b64_e32 v[102:103], 0
	v_mov_b64_e32 v[104:105], 0
	v_mov_b64_e32 v[106:107], 0
	v_mov_b64_e32 v[108:109], 0
	v_mov_b64_e32 v[110:111], 0
	v_mov_b64_e32 v[112:113], 0
	v_mov_b64_e32 v[114:115], 0
	v_mov_b64_e32 v[116:117], 0
	v_mov_b64_e32 v[118:119], 0
	v_mov_b64_e32 v[120:121], 0
	v_mov_b64_e32 v[122:123], 0
	v_mov_b64_e32 v[124:125], 0
	v_mov_b64_e32 v[126:127], 0
	v_mov_b64_e32 v[128:129], 0
	.p2align	6
	s_nop 0
	s_nop 0
	s_nop 0
	s_nop 0
	s_nop 0
	s_nop 0
	s_nop 0
	s_nop 0
	s_nop 0
	s_nop 0
	s_nop 0

;   __device__ __forceinline__ const char* aptr(const Unit& u) const { return s.aptr(u); }
;   __device__ __forceinline__ const char* bptr(const Unit& u) const { return s.bptr(u); }
;   __device__ __forceinline__ bool next(int i, Unit& u) const { if (i) return false; u = u0; return true; }
; template <class Epi, class Sched>
; __device__ __forceinline__ void gemm_phase(PG8_LAS unsigned char* lds, const int lda, const int ldb, const Sched& S, const Epi& E) {
;     ...
;     const bool has_next = S.next(ui + 1, nxt);
;     const char* nA = has_next ? S.aptr(nxt) : cA; const char* nB = has_next ? S.bptr(nxt) : cB;
; #pragma unroll 1
;     for (int t = 0; t < nt; t += 2) {
;       const bool last = (t == nt - 2);
;       const char* a1 = cA + (size_t)(t + 1) * kstep;
;       const char* a2 = last ? nA : cA + (size_t)(t + 2) * kstep; const char* b2 = last ? nB : cB + (size_t)(t + 2) * kstep;
;     ...
;     for (int a = 0; a < 2; ++a)
; #pragma unroll
;       for (int b = 0; b < 2; ++b)
; #pragma unroll
;         for (int m = 0; m < 4; ++m)
; #pragma unroll
;           for (int n = 0; n < 2; ++n) acc[a][b][m][n] = (f32x4){0.f, 0.f, 0.f, 0.f};
.LBB0_1087:
	v_mov_b64_e32 v[2:3], 0x100
	s_ashr_i32 s7, s6, 31
	v_cmp_lt_i64_e32 vcc, s[8:9], v[2:3]
	s_lshl_b64 s[8:9], s[6:7], 21
	v_readlane_b32 s1, v254, 41
	s_add_u32 s8, s1, s8
	v_readlane_b32 s1, v254, 42
	s_addc_u32 s9, s1, s9
	s_and_b64 s[10:11], vcc, exec
	s_cselect_b32 s7, s9, s15
	s_cselect_b32 s13, s8, s14
	s_ashr_i32 s1, s0, 31
	s_lshl_b64 s[10:11], s[0:1], 21
	s_add_u32 s10, s69, s10
	v_readlane_b32 s1, v254, 40
	s_addc_u32 s11, s1, s11
	s_and_b64 s[18:19], vcc, exec
	s_cselect_b32 s1, s11, s17
	s_cselect_b32 s29, s10, s16
	s_add_u32 s14, s14, 0x100080
	s_addc_u32 s15, s15, 0
	s_add_u32 s30, s16, 0x100
	v_mov_b32_e32 v2, 0
	s_addc_u32 s31, s17, 0
	s_mov_b32 s34, -2
	v_mov_b32_e32 v3, v2
	v_mov_b64_e32 v[4:5], 0
	v_mov_b64_e32 v[6:7], 0
	v_mov_b64_e32 v[8:9], 0
	v_mov_b64_e32 v[10:11], 0
	v_mov_b64_e32 v[12:13], 0
	v_mov_b64_e32 v[14:15], 0
	v_mov_b64_e32 v[16:17], 0
	v_mov_b64_e32 v[18:19], 0
	v_mov_b64_e32 v[20:21], 0
	v_mov_b64_e32 v[22:23], 0
	v_mov_b64_e32 v[24:25], 0
	v_mov_b64_e32 v[26:27], 0
	v_mov_b64_e32 v[28:29], 0
	v_mov_b64_e32 v[30:31], 0
	v_mov_b64_e32 v[32:33], 0
	v_mov_b64_e32 v[34:35], 0
	v_mov_b64_e32 v[36:37], 0
	v_mov_b64_e32 v[38:39], 0
	v_mov_b64_e32 v[40:41], 0
	v_mov_b64_e32 v[42:43], 0
	v_mov_b64_e32 v[44:45], 0
	v_mov_b64_e32 v[46:47], 0
	v_mov_b64_e32 v[48:49], 0
	v_mov_b64_e32 v[50:51], 0
	v_mov_b64_e32 v[52:53], 0
	v_mov_b64_e32 v[54:55], 0
	v_mov_b64_e32 v[56:57], 0
	v_mov_b64_e32 v[58:59], 0
	v_mov_b64_e32 v[60:61], 0
	v_mov_b64_e32 v[62:63], 0
	v_mov_b64_e32 v[64:65], 0
	v_mov_b64_e32 v[66:67], 0
	v_mov_b64_e32 v[68:69], 0
	v_mov_b64_e32 v[70:71], 0
	v_mov_b64_e32 v[72:73], 0
	v_mov_b64_e32 v[74:75], 0
	v_mov_b64_e32 v[76:77], 0
	v_mov_b64_e32 v[78:79], 0
	v_mov_b64_e32 v[80:81], 0
	v_mov_b64_e32 v[82:83], 0
	v_mov_b64_e32 v[84:85], 0
	v_mov_b64_e32 v[86:87], 0
	v_mov_b64_e32 v[88:89], 0
	v_mov_b64_e32 v[90:91], 0
	v_mov_b64_e32 v[92:93], 0
	v_mov_b64_e32 v[94:95], 0
	v_mov_b64_e32 v[96:97], 0
	v_mov_b64_e32 v[98:99], 0
	v_mov_b64_e32 v[100:101], 0
	v_mov_b64_e32 v[102:103], 0
	v_mov_b64_e32 v[104:105], 0
	v_mov_b64_e32 v[106:107], 0
	v_mov_b64_e32 v[108:109], 0
	v_mov_b64_e32 v[110:111], 0
	v_mov_b64_e32 v[112:113], 0
	v_mov_b64_e32 v[114:115], 0
	v_mov_b64_e32 v[116:117], 0
	v_mov_b64_e32 v[118:119], 0
	v_mov_b64_e32 v[120:121], 0
	v_mov_b64_e32 v[122:123], 0
	v_mov_b64_e32 v[124:125], 0
	v_mov_b64_e32 v[126:127], 0
	v_mov_b64_e32 v[128:129], 0
	.p2align	6
	s_nop 0
	s_nop 0
	s_nop 0
	s_nop 0
	s_nop 0
	s_nop 0
	s_nop 0
	s_nop 0
	s_nop 0
	s_nop 0
	s_nop 0

;   __device__ __forceinline__ const char* aptr(const Unit& u) const { return s.aptr(u); }
;   __device__ __forceinline__ const char* bptr(const Unit& u) const { return s.bptr(u); }
;   __device__ __forceinline__ bool next(int i, Unit& u) const { if (i) return false; u = u0; return true; }
; template <class Epi, class Sched>
; __device__ __forceinline__ void gemm_phase(PG8_LAS unsigned char* lds, const int lda, const int ldb, const Sched& S, const Epi& E) {
;     ...
;     const bool has_next = S.next(ui + 1, nxt);
;     const char* nA = has_next ? S.aptr(nxt) : cA; const char* nB = has_next ? S.bptr(nxt) : cB;
; #pragma unroll 1
;     for (int t = 0; t < nt; t += 2) {
;       const bool last = (t == nt - 2);
;       const char* a1 = cA + (size_t)(t + 1) * kstep;
;       const char* a2 = last ? nA : cA + (size_t)(t + 2) * kstep; const char* b2 = last ? nB : cB + (size_t)(t + 2) * kstep;
;     ...
;     for (int a = 0; a < 2; ++a)
; #pragma unroll
;       for (int b = 0; b < 2; ++b)
; #pragma unroll
;         for (int m = 0; m < 4; ++m)
; #pragma unroll
;           for (int n = 0; n < 2; ++n) acc[a][b][m][n] = (f32x4){0.f, 0.f, 0.f, 0.f};
.LBB0_1411:
	s_add_i32 s11, s43, -2
	s_add_u32 s14, s14, 0x40080
	s_addc_u32 s15, s15, 0
	s_add_u32 s22, s18, 0x100
	v_mov_b32_e32 v2, 0
	s_addc_u32 s23, s19, 0
	s_mov_b32 s18, 0
	v_mov_b32_e32 v3, v2
	v_mov_b64_e32 v[4:5], 0
	v_mov_b64_e32 v[6:7], 0
	v_mov_b64_e32 v[8:9], 0
	v_mov_b64_e32 v[10:11], 0
	v_mov_b64_e32 v[12:13], 0
	v_mov_b64_e32 v[14:15], 0
	v_mov_b64_e32 v[16:17], 0
	v_mov_b64_e32 v[18:19], 0
	v_mov_b64_e32 v[20:21], 0
	v_mov_b64_e32 v[22:23], 0
	v_mov_b64_e32 v[24:25], 0
	v_mov_b64_e32 v[26:27], 0
	v_mov_b64_e32 v[28:29], 0
	v_mov_b64_e32 v[30:31], 0
	v_mov_b64_e32 v[32:33], 0
	v_mov_b64_e32 v[34:35], 0
	v_mov_b64_e32 v[36:37], 0
	v_mov_b64_e32 v[38:39], 0
	v_mov_b64_e32 v[40:41], 0
	v_mov_b64_e32 v[42:43], 0
	v_mov_b64_e32 v[44:45], 0
	v_mov_b64_e32 v[46:47], 0
	v_mov_b64_e32 v[48:49], 0
	v_mov_b64_e32 v[50:51], 0
	v_mov_b64_e32 v[52:53], 0
	v_mov_b64_e32 v[54:55], 0
	v_mov_b64_e32 v[56:57], 0
	v_mov_b64_e32 v[58:59], 0
	v_mov_b64_e32 v[60:61], 0
	v_mov_b64_e32 v[62:63], 0
	v_mov_b64_e32 v[64:65], 0
	v_mov_b64_e32 v[66:67], 0
	v_mov_b64_e32 v[68:69], 0
	v_mov_b64_e32 v[70:71], 0
	v_mov_b64_e32 v[72:73], 0
	v_mov_b64_e32 v[74:75], 0
	v_mov_b64_e32 v[76:77], 0
	v_mov_b64_e32 v[78:79], 0
	v_mov_b64_e32 v[80:81], 0
	v_mov_b64_e32 v[82:83], 0
	v_mov_b64_e32 v[84:85], 0
	v_mov_b64_e32 v[86:87], 0
	v_mov_b64_e32 v[88:89], 0
	v_mov_b64_e32 v[90:91], 0
	v_mov_b64_e32 v[92:93], 0
	v_mov_b64_e32 v[94:95], 0
	v_mov_b64_e32 v[96:97], 0
	v_mov_b64_e32 v[98:99], 0
	v_mov_b64_e32 v[100:101], 0
	v_mov_b64_e32 v[102:103], 0
	v_mov_b64_e32 v[104:105], 0
	v_mov_b64_e32 v[106:107], 0
	v_mov_b64_e32 v[108:109], 0
	v_mov_b64_e32 v[110:111], 0
	v_mov_b64_e32 v[112:113], 0
	v_mov_b64_e32 v[114:115], 0
	v_mov_b64_e32 v[116:117], 0
	v_mov_b64_e32 v[118:119], 0
	v_mov_b64_e32 v[120:121], 0
	v_mov_b64_e32 v[122:123], 0
	v_mov_b64_e32 v[124:125], 0
	v_mov_b64_e32 v[126:127], 0
	v_mov_b64_e32 v[128:129], 0
	.p2align	6
	s_nop 0
	s_nop 0
	s_nop 0
	s_nop 0
	s_nop 0
	s_nop 0
	s_nop 0
	s_nop 0
	s_nop 0
	s_nop 0
	s_nop 0

;   __device__ __forceinline__ const char* aptr(const Unit& u) const { return s.aptr(u); }
;   __device__ __forceinline__ const char* bptr(const Unit& u) const { return s.bptr(u); }
;   __device__ __forceinline__ bool next(int i, Unit& u) const { if (i) return false; u = u0; return true; }
; template <class Epi, class Sched>
; __device__ __forceinline__ void gemm_phase(PG8_LAS unsigned char* lds, const int lda, const int ldb, const Sched& S, const Epi& E) {
;     ...
;     const bool has_next = S.next(ui + 1, nxt);
;     const char* nA = has_next ? S.aptr(nxt) : cA; const char* nB = has_next ? S.bptr(nxt) : cB;
; #pragma unroll 1
;     for (int t = 0; t < nt; t += 2) {
;       const bool last = (t == nt - 2);
;       const char* a1 = cA + (size_t)(t + 1) * kstep;
;       const char* a2 = last ? nA : cA + (size_t)(t + 2) * kstep; const char* b2 = last ? nB : cB + (size_t)(t + 2) * kstep;
;     ...
;     for (int a = 0; a < 2; ++a)
; #pragma unroll
;       for (int b = 0; b < 2; ++b)
; #pragma unroll
;         for (int m = 0; m < 4; ++m)
; #pragma unroll
;           for (int n = 0; n < 2; ++n) acc[a][b][m][n] = (f32x4){0.f, 0.f, 0.f, 0.f};
.LBB0_1481:
	v_mov_b64_e32 v[2:3], s[8:9]
	s_ashr_i32 s11, s10, 31
	v_cmp_lt_i64_e32 vcc, s[12:13], v[2:3]
	s_lshl_b64 s[12:13], s[10:11], 19
	s_add_u32 s12, s84, s12
	s_addc_u32 s13, s85, s13
	s_and_b64 s[14:15], vcc, exec
	s_cselect_b32 s11, s13, s19
	s_cselect_b32 s50, s12, s18
	s_ashr_i32 s1, s0, 31
	s_lshl_b64 s[14:15], s[0:1], 19
	s_add_u32 s14, s30, s14
	s_addc_u32 s15, s31, s15
	s_and_b64 s[22:23], vcc, exec
	s_cselect_b32 s1, s15, s21
	s_cselect_b32 s51, s14, s20
	s_add_u32 s52, s20, 0x100
	v_mov_b32_e32 v2, 0
	s_addc_u32 s53, s21, 0
	s_mov_b32 s54, -2
	v_mov_b32_e32 v3, v2
	v_mov_b64_e32 v[4:5], 0
	v_mov_b64_e32 v[6:7], 0
	v_mov_b64_e32 v[8:9], 0
	v_mov_b64_e32 v[10:11], 0
	v_mov_b64_e32 v[12:13], 0
	v_mov_b64_e32 v[14:15], 0
	v_mov_b64_e32 v[16:17], 0
	v_mov_b64_e32 v[18:19], 0
	v_mov_b64_e32 v[20:21], 0
	v_mov_b64_e32 v[22:23], 0
	v_mov_b64_e32 v[24:25], 0
	v_mov_b64_e32 v[26:27], 0
	v_mov_b64_e32 v[28:29], 0
	v_mov_b64_e32 v[30:31], 0
	v_mov_b64_e32 v[32:33], 0
	v_mov_b64_e32 v[34:35], 0
	v_mov_b64_e32 v[36:37], 0
	v_mov_b64_e32 v[38:39], 0
	v_mov_b64_e32 v[40:41], 0
	v_mov_b64_e32 v[42:43], 0
	v_mov_b64_e32 v[44:45], 0
	v_mov_b64_e32 v[46:47], 0
	v_mov_b64_e32 v[48:49], 0
	v_mov_b64_e32 v[50:51], 0
	v_mov_b64_e32 v[52:53], 0
	v_mov_b64_e32 v[54:55], 0
	v_mov_b64_e32 v[56:57], 0
	v_mov_b64_e32 v[58:59], 0
	v_mov_b64_e32 v[60:61], 0
	v_mov_b64_e32 v[62:63], 0
	v_mov_b64_e32 v[64:65], 0
	v_mov_b64_e32 v[66:67], 0
	v_mov_b64_e32 v[68:69], 0
	v_mov_b64_e32 v[70:71], 0
	v_mov_b64_e32 v[72:73], 0
	v_mov_b64_e32 v[74:75], 0
	v_mov_b64_e32 v[76:77], 0
	v_mov_b64_e32 v[78:79], 0
	v_mov_b64_e32 v[80:81], 0
	v_mov_b64_e32 v[82:83], 0
	v_mov_b64_e32 v[84:85], 0
	v_mov_b64_e32 v[86:87], 0
	v_mov_b64_e32 v[88:89], 0
	v_mov_b64_e32 v[90:91], 0
	v_mov_b64_e32 v[92:93], 0
	v_mov_b64_e32 v[94:95], 0
	v_mov_b64_e32 v[96:97], 0
	v_mov_b64_e32 v[98:99], 0
	v_mov_b64_e32 v[100:101], 0
	v_mov_b64_e32 v[102:103], 0
	v_mov_b64_e32 v[104:105], 0
	v_mov_b64_e32 v[106:107], 0
	v_mov_b64_e32 v[108:109], 0
	v_mov_b64_e32 v[110:111], 0
	v_mov_b64_e32 v[112:113], 0
	v_mov_b64_e32 v[114:115], 0
	v_mov_b64_e32 v[116:117], 0
	v_mov_b64_e32 v[118:119], 0
	v_mov_b64_e32 v[120:121], 0
	v_mov_b64_e32 v[122:123], 0
	v_mov_b64_e32 v[124:125], 0
	v_mov_b64_e32 v[126:127], 0
	v_mov_b64_e32 v[128:129], 0
	.p2align	6
	s_nop 0
	s_nop 0
	s_nop 0
	s_nop 0
	s_nop 0
	s_nop 0
	s_nop 0
	s_nop 0
	s_nop 0
	s_nop 0
	s_nop 0

;   __device__ __forceinline__ const char* aptr(const Unit& u) const { return s.aptr(u); }
;   __device__ __forceinline__ const char* bptr(const Unit& u) const { return s.bptr(u); }
;   __device__ __forceinline__ bool next(int i, Unit& u) const { if (i) return false; u = u0; return true; }
; template <class Epi, class Sched>
; __device__ __forceinline__ void gemm_phase(PG8_LAS unsigned char* lds, const int lda, const int ldb, const Sched& S, const Epi& E) {
;     ...
;     const bool has_next = S.next(ui + 1, nxt);
;     const char* nA = has_next ? S.aptr(nxt) : cA; const char* nB = has_next ? S.bptr(nxt) : cB;
; #pragma unroll 1
;     for (int t = 0; t < nt; t += 2) {
;       const bool last = (t == nt - 2);
;       const char* a1 = cA + (size_t)(t + 1) * kstep;
;       const char* a2 = last ? nA : cA + (size_t)(t + 2) * kstep; const char* b2 = last ? nB : cB + (size_t)(t + 2) * kstep;
;     ...
;     for (int a = 0; a < 2; ++a)
; #pragma unroll
;       for (int b = 0; b < 2; ++b)
; #pragma unroll
;         for (int m = 0; m < 4; ++m)
; #pragma unroll
;           for (int n = 0; n < 2; ++n) acc[a][b][m][n] = (f32x4){0.f, 0.f, 0.f, 0.f};
.LBB0_1603:
	v_mov_b64_e32 v[2:3], s[2:3]
	s_ashr_i32 s11, s10, 31
	v_cmp_lt_i64_e32 vcc, s[12:13], v[2:3]
	s_lshl_b64 s[12:13], s[10:11], 19
	s_add_u32 s12, s58, s12
	s_addc_u32 s13, s59, s13
	s_and_b64 s[14:15], vcc, exec
	s_cselect_b32 s11, s13, s19
	s_cselect_b32 s42, s12, s18
	s_ashr_i32 s1, s0, 31
	s_lshl_b64 s[14:15], s[0:1], 19
	s_add_u32 s14, s24, s14
	s_addc_u32 s15, s25, s15
	s_and_b64 s[22:23], vcc, exec
	s_cselect_b32 s1, s15, s21
	s_cselect_b32 s43, s14, s20
	s_add_u32 s18, s18, 0x40080
	s_addc_u32 s19, s19, 0
	s_add_u32 s44, s20, 0x100
	v_mov_b32_e32 v2, 0
	s_addc_u32 s45, s21, 0
	s_mov_b32 s46, -2
	v_mov_b32_e32 v3, v2
	v_mov_b64_e32 v[4:5], 0
	v_mov_b64_e32 v[6:7], 0
	v_mov_b64_e32 v[8:9], 0
	v_mov_b64_e32 v[10:11], 0
	v_mov_b64_e32 v[12:13], 0
	v_mov_b64_e32 v[14:15], 0
	v_mov_b64_e32 v[16:17], 0
	v_mov_b64_e32 v[18:19], 0
	v_mov_b64_e32 v[20:21], 0
	v_mov_b64_e32 v[22:23], 0
	v_mov_b64_e32 v[24:25], 0
	v_mov_b64_e32 v[26:27], 0
	v_mov_b64_e32 v[28:29], 0
	v_mov_b64_e32 v[30:31], 0
	v_mov_b64_e32 v[32:33], 0
	v_mov_b64_e32 v[34:35], 0
	v_mov_b64_e32 v[36:37], 0
	v_mov_b64_e32 v[38:39], 0
	v_mov_b64_e32 v[40:41], 0
	v_mov_b64_e32 v[42:43], 0
	v_mov_b64_e32 v[44:45], 0
	v_mov_b64_e32 v[46:47], 0
	v_mov_b64_e32 v[48:49], 0
	v_mov_b64_e32 v[50:51], 0
	v_mov_b64_e32 v[52:53], 0
	v_mov_b64_e32 v[54:55], 0
	v_mov_b64_e32 v[56:57], 0
	v_mov_b64_e32 v[58:59], 0
	v_mov_b64_e32 v[60:61], 0
	v_mov_b64_e32 v[62:63], 0
	v_mov_b64_e32 v[64:65], 0
	v_mov_b64_e32 v[66:67], 0
	v_mov_b64_e32 v[68:69], 0
	v_mov_b64_e32 v[70:71], 0
	v_mov_b64_e32 v[72:73], 0
	v_mov_b64_e32 v[74:75], 0
	v_mov_b64_e32 v[76:77], 0
	v_mov_b64_e32 v[78:79], 0
	v_mov_b64_e32 v[80:81], 0
	v_mov_b64_e32 v[82:83], 0
	v_mov_b64_e32 v[84:85], 0
	v_mov_b64_e32 v[86:87], 0
	v_mov_b64_e32 v[88:89], 0
	v_mov_b64_e32 v[90:91], 0
	v_mov_b64_e32 v[92:93], 0
	v_mov_b64_e32 v[94:95], 0
	v_mov_b64_e32 v[96:97], 0
	v_mov_b64_e32 v[98:99], 0
	v_mov_b64_e32 v[100:101], 0
	v_mov_b64_e32 v[102:103], 0
	v_mov_b64_e32 v[104:105], 0
	v_mov_b64_e32 v[106:107], 0
	v_mov_b64_e32 v[108:109], 0
	v_mov_b64_e32 v[110:111], 0
	v_mov_b64_e32 v[112:113], 0
	v_mov_b64_e32 v[114:115], 0
	v_mov_b64_e32 v[116:117], 0
	v_mov_b64_e32 v[118:119], 0
	v_mov_b64_e32 v[120:121], 0
	v_mov_b64_e32 v[122:123], 0
	v_mov_b64_e32 v[124:125], 0
	v_mov_b64_e32 v[126:127], 0
	v_mov_b64_e32 v[128:129], 0
	.p2align	6
	s_nop 0
	s_nop 0
	s_nop 0
	s_nop 0
	s_nop 0
	s_nop 0
	s_nop 0
	s_nop 0
	s_nop 0
	s_nop 0
	s_nop 0

; template <class Epi, class Sched>
; __device__ __forceinline__ void gemm_phase(PG8_LAS unsigned char* lds, const int lda, const int ldb, const Sched& S, const Epi& E) {
;     ...
;     for (int a = 0; a < 2; ++a)
; #pragma unroll
;       for (int b = 0; b < 2; ++b)
; #pragma unroll
;         for (int m = 0; m < 4; ++m)
; #pragma unroll
;           for (int n = 0; n < 2; ++n) acc[a][b][m][n] = (f32x4){0.f, 0.f, 0.f, 0.f};
.LBB0_1672:
	s_add_u32 s39, s12, 0x100
	v_mov_b32_e32 v2, 0
	s_addc_u32 s40, s13, 0
	s_mov_b32 s41, -2
	v_mov_b32_e32 v3, v2
	v_mov_b64_e32 v[4:5], 0
	v_mov_b64_e32 v[6:7], 0
	v_mov_b64_e32 v[8:9], 0
	v_mov_b64_e32 v[10:11], 0
	v_mov_b64_e32 v[12:13], 0
	v_mov_b64_e32 v[14:15], 0
	v_mov_b64_e32 v[16:17], 0
	v_mov_b64_e32 v[18:19], 0
	v_mov_b64_e32 v[20:21], 0
	v_mov_b64_e32 v[22:23], 0
	v_mov_b64_e32 v[24:25], 0
	v_mov_b64_e32 v[26:27], 0
	v_mov_b64_e32 v[28:29], 0
	v_mov_b64_e32 v[30:31], 0
	v_mov_b64_e32 v[32:33], 0
	v_mov_b64_e32 v[34:35], 0
	v_mov_b64_e32 v[36:37], 0
	v_mov_b64_e32 v[38:39], 0
	v_mov_b64_e32 v[40:41], 0
	v_mov_b64_e32 v[42:43], 0
	v_mov_b64_e32 v[44:45], 0
	v_mov_b64_e32 v[46:47], 0
	v_mov_b64_e32 v[48:49], 0
	v_mov_b64_e32 v[50:51], 0
	v_mov_b64_e32 v[52:53], 0
	v_mov_b64_e32 v[54:55], 0
	v_mov_b64_e32 v[56:57], 0
	v_mov_b64_e32 v[58:59], 0
	v_mov_b64_e32 v[60:61], 0
	v_mov_b64_e32 v[62:63], 0
	v_mov_b64_e32 v[64:65], 0
	v_mov_b64_e32 v[66:67], 0
	v_mov_b64_e32 v[68:69], 0
	v_mov_b64_e32 v[70:71], 0
	v_mov_b64_e32 v[72:73], 0
	v_mov_b64_e32 v[74:75], 0
	v_mov_b64_e32 v[76:77], 0
	v_mov_b64_e32 v[78:79], 0
	v_mov_b64_e32 v[80:81], 0
	v_mov_b64_e32 v[82:83], 0
	v_mov_b64_e32 v[84:85], 0
	v_mov_b64_e32 v[86:87], 0
	v_mov_b64_e32 v[88:89], 0
	v_mov_b64_e32 v[90:91], 0
	v_mov_b64_e32 v[92:93], 0
	v_mov_b64_e32 v[94:95], 0
	v_mov_b64_e32 v[96:97], 0
	v_mov_b64_e32 v[98:99], 0
	v_mov_b64_e32 v[100:101], 0
	v_mov_b64_e32 v[102:103], 0
	v_mov_b64_e32 v[104:105], 0
	v_mov_b64_e32 v[106:107], 0
	v_mov_b64_e32 v[108:109], 0
	v_mov_b64_e32 v[110:111], 0
	v_mov_b64_e32 v[112:113], 0
	v_mov_b64_e32 v[114:115], 0
	v_mov_b64_e32 v[116:117], 0
	v_mov_b64_e32 v[118:119], 0
	v_mov_b64_e32 v[120:121], 0
	v_mov_b64_e32 v[122:123], 0
	v_mov_b64_e32 v[124:125], 0
	v_mov_b64_e32 v[126:127], 0
	v_mov_b64_e32 v[128:129], 0
	.p2align	6
	s_nop 0
	s_nop 0
	s_nop 0
	s_nop 0
	s_nop 0
	s_nop 0
	s_nop 0
	s_nop 0
	s_nop 0
	s_nop 0
	s_nop 0
